# diff attention loop: paired lgkmcnt waits merged, scalar row-sum add pairs packed, zero-initialising adds folded into the first accumulate
# speedup vs baseline: 1.0121x; 1.0026x over previous
; DI void diff_mfma_phase(const Args& A, int wave_s, int l, bool need_ctx, LAS unsigned char* lds) {
;     ...
;         for (int it = 0; it < ntiles; ++it) {
;             const int cur = it & 1;
;             if (it + 1 < ntiles) { const int kr0 = (it + 1 < 64 ? kbase0 : kbase1) + (it + 1) * DT_ROWS;
;                 const char* kb_ = (const char*)(C.P + (size_t)kr0 * INW + CC_K + hd * 64);
;                 kreg[0] = *(const v4u*)(kb_ + sgoff); kreg[1] = *(const v4u*)(kb_ + (size_t)64 * INW * 2 + sgoff); }
;             LAS unsigned char* Kb = lds + cur * DT_IMG; LAS unsigned char* Vb = lds + VOFF0 + cur * DV_IMG;
;             LAS unsigned char* kl = Kb + r * KV_PITCH + h * 16;
;             f32x16 Sc;
;             { const bf16x8 kA0 = *(LAS bf16x8*)(kl), kA1 = *(LAS bf16x8*)(kl + 32); Sc = MFMA32(kA0, Qf[0][0], negM); Sc = MFMA32(kA1, Qf[0][1], Sc); }
; #pragma unroll
;             for (int g = 0; g < 8; ++g) {
;                 const int c = g & 1, sub = g >> 1;
;                 bf16x8 kB0, kB1; f32x16 Sn;
;                 if (g < 7) { LAS unsigned char* kp = kl + (32 * ((g + 1) >> 1)) * KV_PITCH + (c ^ 1) * 64; kB0 = *(LAS bf16x8*)(kp); kB1 = *(LAS bf16x8*)(kp + 32); }
;                 if (c == 0) { O[1][0] = MFMA32(Vs[0], Pp0, O[1][0]); O[1][1] = MFMA32(Vs[2], Pp0, O[1][1]); O[1][0] = MFMA32(Vs[1], Pp1, O[1][0]); O[1][1] = MFMA32(Vs[3], Pp1, O[1][1]); }
;                 else        { O[0][0] = MFMA32(Vs[0], Pp0, O[0][0]); O[0][1] = MFMA32(Vs[2], Pp0, O[0][1]); O[0][0] = MFMA32(Vs[1], Pp1, O[0][0]); O[0][1] = MFMA32(Vs[3], Pp1, O[0][1]); }
;                 float t = 0.f;
; #pragma unroll
;                 for (int i = 0; i < 8; ++i) { Sc[i] = __builtin_amdgcn_exp2f(Sc[i]); t += Sc[i]; }
;                 const bf16x8 Pn0 = PACK8(Sc, 0);
;                 __builtin_amdgcn_sched_barrier(0);
;                 if (g < 7) { Sn = MFMA32(kB0, Qf[c ^ 1][0], negM); Sn = MFMA32(kB1, Qf[c ^ 1][1], Sn); }
;                 __builtin_amdgcn_sched_barrier(0);
;                 if (c == 0) { LAS unsigned char* vp = Vb + (32 * sub) * VP + voff; Vs[0] = tr_pairV(vp); Vs[1] = tr_pairV(vp + 16 * VP); Vs[2] = tr_pairV(vp + 64); Vs[3] = tr_pairV(vp + 16 * VP + 64); }
; #pragma unroll
;                 for (int i = 8; i < 16; ++i) { Sc[i] = __builtin_amdgcn_exp2f(Sc[i]); t += Sc[i]; }
;                 if (c == 0) ls0 += t; else ls1 += t;
.LBB0_406:
	s_and_b32 s18, s15, 1
	s_mul_i32 s9, s18, 0x4800
	v_add_u32_e32 v160, s9, v218
	ds_read_b128 v[64:67], v160
	ds_read_b128 v[80:83], v160 offset:32
	s_add_i32 s14, s15, 1
	s_cmp_lt_u32 s15, 63
	s_cselect_b32 s9, s10, s12
	s_ashr_i32 s15, s9, 31
	s_add_u32 s9, s6, s9
	s_addc_u32 s15, s7, s15
	s_mul_hi_u32 s16, s9, 0x1800
	s_waitcnt lgkmcnt(1)
	v_mfma_f32_32x32x16_bf16 v[64:79], v[64:67], v[108:111], 0
	s_mulk_i32 s15, 0x1800
	s_mulk_i32 s9, 0x1800
	s_add_i32 s16, s16, s15
	s_add_u32 s15, s84, s9
	s_addc_u32 s17, s85, s16
	s_lshl_b32 s9, s11, 1
	s_add_u32 s16, s15, s9
	s_addc_u32 s17, s17, 0
	s_waitcnt lgkmcnt(0)
	v_mfma_f32_32x32x16_bf16 v[64:79], v[80:83], v[104:107], v[64:79]
	v_lshl_add_u64 v[80:81], s[16:17], 0, v[138:139]
	v_add_co_u32_e32 v128, vcc, s76, v80
	s_mul_i32 s15, s18, 0x6000
	s_nop 0
	v_addc_co_u32_e32 v129, vcc, 0, v81, vcc
	v_add_co_u32_e32 v132, vcc, s3, v80
	v_mfma_f32_32x32x16_bf16 v[16:31], v[120:123], v[88:91], v[16:31]
	s_nop 0
	v_addc_co_u32_e32 v133, vcc, 0, v81, vcc
	s_nop 2
	v_exp_f32_e32 v130, v64
	v_exp_f32_e32 v134, v65
	v_exp_f32_e32 v164, v66
	v_exp_f32_e32 v184, v67
	v_exp_f32_e32 v186, v68
	v_mfma_f32_32x32x16_bf16 v[0:15], v[124:127], v[88:91], v[0:15]
	global_load_dwordx4 v[120:123], v[128:129], off offset:1024
	global_load_dwordx4 v[124:127], v[132:133], off offset:1024
	v_exp_f32_e32 v188, v69
	v_exp_f32_e32 v190, v70
	v_exp_f32_e32 v192, v71
	v_add_u32_e32 v147, s15, v219
	s_xor_b32 s15, s18, 1
	s_mul_i32 s16, s15, 0x4800
	v_mfma_f32_32x32x16_bf16 v[16:31], v[116:119], v[92:95], v[16:31]
	ds_read_b128 v[80:83], v160 offset:64
	ds_read_b128 v[116:119], v160 offset:96
	s_add_i32 s16, s16, 0
	v_add3_u32 v166, s16, v214, v212
	v_add3_u32 v167, s16, v215, v212
	v_cvt_pk_bf16_f32 v64, v130, v134
	v_cvt_pk_bf16_f32 v65, v164, v184
	v_cvt_pk_bf16_f32 v66, v186, v188
	v_mfma_f32_32x32x16_bf16 v[0:15], v[112:115], v[92:95], v[0:15]
	v_cvt_pk_bf16_f32 v67, v190, v192
	s_waitcnt lgkmcnt(0)
	v_mfma_f32_32x32x16_bf16 v[80:95], v[80:83], v[100:103], 0
	v_mfma_f32_32x32x16_bf16 v[80:95], v[116:119], v[96:99], v[80:95]
	ds_read_b64_tr_b16 v[68:69], v147 offset:36864
	ds_read_b64_tr_b16 v[70:71], v147 offset:38400
	ds_read_b64_tr_b16 v[114:115], v147 offset:38464
	ds_read_b64_tr_b16 v[112:113], v147 offset:36928
	ds_read_b64_tr_b16 v[116:117], v147 offset:39936
	ds_read_b64_tr_b16 v[118:119], v147 offset:41472
	ds_read_b64_tr_b16 v[174:175], v147 offset:41536
	ds_read_b64_tr_b16 v[172:173], v147 offset:40000
	v_exp_f32_e32 v194, v72
	v_exp_f32_e32 v170, v73
	v_exp_f32_e32 v168, v74
	v_exp_f32_e32 v158, v75
	v_exp_f32_e32 v156, v76
	v_exp_f32_e32 v154, v77
	v_exp_f32_e32 v152, v78
	v_exp_f32_e32 v150, v79
	v_cvt_pk_bf16_f32 v72, v194, v170
	v_cvt_pk_bf16_f32 v73, v168, v158
	v_cvt_pk_bf16_f32 v74, v156, v154
	v_cvt_pk_bf16_f32 v75, v152, v150
	s_waitcnt lgkmcnt(6)
	v_mfma_f32_32x32x16_bf16 v[48:63], v[68:71], v[64:67], v[48:63]
	v_exp_f32_e32 v131, v80
	v_exp_f32_e32 v135, v81
	v_exp_f32_e32 v165, v82
	v_exp_f32_e32 v185, v83
	v_exp_f32_e32 v187, v84
	v_exp_f32_e32 v189, v85
	v_exp_f32_e32 v191, v86
	s_waitcnt lgkmcnt(4)
	v_mfma_f32_32x32x16_bf16 v[32:47], v[112:115], v[64:67], v[32:47]
	ds_read_b128 v[64:67], v160 offset:4608
	ds_read_b128 v[176:179], v160 offset:4640
	v_exp_f32_e32 v193, v87
	v_cvt_pk_bf16_f32 v180, v131, v135
	v_cvt_pk_bf16_f32 v181, v165, v185
	v_cvt_pk_bf16_f32 v182, v187, v189
	v_cvt_pk_bf16_f32 v183, v191, v193
	s_waitcnt lgkmcnt(2)
	v_mfma_f32_32x32x16_bf16 v[48:63], v[116:119], v[72:75], v[48:63]
	v_mfma_f32_32x32x16_bf16 v[32:47], v[172:175], v[72:75], v[32:47]
	s_waitcnt lgkmcnt(0)
	v_mfma_f32_32x32x16_bf16 v[72:87], v[64:67], v[108:111], 0
	v_mfma_f32_32x32x16_bf16 v[72:87], v[176:179], v[104:107], v[72:87]
	v_exp_f32_e32 v195, v88
	v_pk_add_f32 v[64:65], v[134:135], v[130:131]
	v_exp_f32_e32 v171, v89
	v_pk_add_f32 v[64:65], v[164:165], v[64:65]
	v_exp_f32_e32 v169, v90
	v_pk_add_f32 v[64:65], v[184:185], v[64:65]
	v_exp_f32_e32 v159, v91
	v_pk_add_f32 v[64:65], v[186:187], v[64:65]
	v_exp_f32_e32 v157, v92
	v_exp_f32_e32 v155, v93
	v_exp_f32_e32 v153, v94
	v_exp_f32_e32 v151, v95
	v_pk_add_f32 v[64:65], v[188:189], v[64:65]
	v_cvt_pk_bf16_f32 v66, v157, v155
	v_pk_add_f32 v[64:65], v[190:191], v[64:65]
	v_cvt_pk_bf16_f32 v67, v153, v151
	v_pk_add_f32 v[64:65], v[192:193], v[64:65]
	s_nop 0
	v_pk_add_f32 v[178:179], v[194:195], v[64:65]
	v_cvt_pk_bf16_f32 v64, v195, v171
	v_cvt_pk_bf16_f32 v65, v169, v159
	v_mfma_f32_32x32x16_bf16 v[16:31], v[68:71], v[180:183], v[16:31]
	ds_read_b128 v[88:91], v160 offset:4672
	ds_read_b128 v[92:95], v160 offset:4704
	v_exp_f32_e32 v130, v72
	v_exp_f32_e32 v134, v73
	v_exp_f32_e32 v164, v74
	v_exp_f32_e32 v208, v75
	v_exp_f32_e32 v210, v76
	v_exp_f32_e32 v222, v77
	v_mfma_f32_32x32x16_bf16 v[0:15], v[112:115], v[180:183], v[0:15]
	v_exp_f32_e32 v224, v78
	v_exp_f32_e32 v226, v79
	v_cvt_pk_bf16_f32 v112, v130, v134
	v_cvt_pk_bf16_f32 v113, v164, v208
	v_cvt_pk_bf16_f32 v114, v210, v222
	v_cvt_pk_bf16_f32 v115, v224, v226
	v_mfma_f32_32x32x16_bf16 v[16:31], v[116:119], v[64:67], v[16:31]
	v_mfma_f32_32x32x16_bf16 v[0:15], v[172:175], v[64:67], v[0:15]
	s_waitcnt lgkmcnt(0)
	v_mfma_f32_32x32x16_bf16 v[64:79], v[88:91], v[100:103], 0
	v_mfma_f32_32x32x16_bf16 v[64:79], v[92:95], v[96:99], v[64:79]
	ds_read_b64_tr_b16 v[116:117], v147 offset:43008
	ds_read_b64_tr_b16 v[118:119], v147 offset:44544
	ds_read_b64_tr_b16 v[194:195], v147 offset:44608
	ds_read_b64_tr_b16 v[192:193], v147 offset:43072
	ds_read_b64_tr_b16 v[196:197], v147 offset:46080
	ds_read_b64_tr_b16 v[198:199], v147 offset:47616
	ds_read_b64_tr_b16 v[202:203], v147 offset:47680
	ds_read_b64_tr_b16 v[200:201], v147 offset:46144
	v_exp_f32_e32 v188, v80
	v_exp_f32_e32 v186, v81
	v_exp_f32_e32 v184, v82
	v_exp_f32_e32 v182, v83
	v_exp_f32_e32 v180, v84
	v_exp_f32_e32 v176, v85
	v_exp_f32_e32 v174, v86
	v_exp_f32_e32 v172, v87
	v_cvt_pk_bf16_f32 v80, v188, v186
	v_cvt_pk_bf16_f32 v81, v184, v182
	v_cvt_pk_bf16_f32 v82, v180, v176
	v_cvt_pk_bf16_f32 v83, v174, v172
	s_waitcnt lgkmcnt(6)
; DI void diff_mfma_phase(const Args& A, int wave_s, int l, bool need_ctx, LAS unsigned char* lds) {
;     ...
;             { const bf16x8 kA0 = *(LAS bf16x8*)(kl), kA1 = *(LAS bf16x8*)(kl + 32); Sc = MFMA32(kA0, Qf[0][0], negM); Sc = MFMA32(kA1, Qf[0][1], Sc); }
; #pragma unroll
;             for (int g = 0; g < 8; ++g) {
;                 const int c = g & 1, sub = g >> 1;
;                 bf16x8 kB0, kB1; f32x16 Sn;
;                 if (g < 7) { LAS unsigned char* kp = kl + (32 * ((g + 1) >> 1)) * KV_PITCH + (c ^ 1) * 64; kB0 = *(LAS bf16x8*)(kp); kB1 = *(LAS bf16x8*)(kp + 32); }
;                 if (c == 0) { O[1][0] = MFMA32(Vs[0], Pp0, O[1][0]); O[1][1] = MFMA32(Vs[2], Pp0, O[1][1]); O[1][0] = MFMA32(Vs[1], Pp1, O[1][0]); O[1][1] = MFMA32(Vs[3], Pp1, O[1][1]); }
;                 else        { O[0][0] = MFMA32(Vs[0], Pp0, O[0][0]); O[0][1] = MFMA32(Vs[2], Pp0, O[0][1]); O[0][0] = MFMA32(Vs[1], Pp1, O[0][0]); O[0][1] = MFMA32(Vs[3], Pp1, O[0][1]); }
;                 float t = 0.f;
; #pragma unroll
;                 for (int i = 0; i < 8; ++i) { Sc[i] = __builtin_amdgcn_exp2f(Sc[i]); t += Sc[i]; }
;                 const bf16x8 Pn0 = PACK8(Sc, 0);
;                 __builtin_amdgcn_sched_barrier(0);
;                 if (g < 7) { Sn = MFMA32(kB0, Qf[c ^ 1][0], negM); Sn = MFMA32(kB1, Qf[c ^ 1][1], Sn); }
;                 __builtin_amdgcn_sched_barrier(0);
;                 if (c == 0) { LAS unsigned char* vp = Vb + (32 * sub) * VP + voff; Vs[0] = tr_pairV(vp); Vs[1] = tr_pairV(vp + 16 * VP); Vs[2] = tr_pairV(vp + 64); Vs[3] = tr_pairV(vp + 16 * VP + 64); }
; #pragma unroll
;                 for (int i = 8; i < 16; ++i) { Sc[i] = __builtin_amdgcn_exp2f(Sc[i]); t += Sc[i]; }
;                 if (c == 0) ls0 += t; else ls1 += t;
;                 Pp0 = Pn0; Pp1 = PACK8(Sc, 1);
;                 if (g < 7) Sc = Sn;
;                 __builtin_amdgcn_sched_barrier(0);
;                 if (g == 3 && it + 1 < ntiles) {
;                     LAS unsigned char* kb2 = lds + (cur ^ 1) * DT_IMG;
;                     *(LAS v4u*)(kb2 + srow * KV_PITCH + sch * 16) = kreg[0]; *(LAS v4u*)(kb2 + (srow + 64) * KV_PITCH + sch * 16) = kreg[1];
;                     const int kr0 = (it + 1 < 64 ? kbase0 : kbase1) + (it + 1) * DT_ROWS;
;                     const char* vb_ = (const char*)(C.P + (size_t)kr0 * INW + CC_V + hd * 64);
	v_mfma_f32_32x32x16_bf16 v[48:63], v[116:119], v[112:115], v[48:63]
	v_exp_f32_e32 v131, v64
	v_exp_f32_e32 v135, v65
	v_exp_f32_e32 v165, v66
	v_exp_f32_e32 v209, v67
	v_exp_f32_e32 v211, v68
	v_exp_f32_e32 v223, v69
	s_waitcnt lgkmcnt(4)
	v_mfma_f32_32x32x16_bf16 v[32:47], v[192:195], v[112:115], v[32:47]
	v_pk_add_f32 v[64:65], v[134:135], v[130:131]
	ds_read_b128 v[84:87], v160 offset:9216
	ds_read_b128 v[204:207], v160 offset:9248
	v_exp_f32_e32 v225, v70
	v_pk_add_f32 v[64:65], v[164:165], v[64:65]
	v_exp_f32_e32 v227, v71
	v_pk_add_f32 v[64:65], v[208:209], v[64:65]
	v_cvt_pk_bf16_f32 v66, v211, v223
	s_waitcnt lgkmcnt(4)
	v_mfma_f32_32x32x16_bf16 v[48:63], v[196:199], v[80:83], v[48:63]
	v_pk_add_f32 v[64:65], v[210:211], v[64:65]
	v_cvt_pk_bf16_f32 v67, v225, v227
	v_pk_add_f32 v[64:65], v[222:223], v[64:65]
	v_pk_add_f32 v[64:65], v[224:225], v[64:65]
	s_nop 0
	v_pk_add_f32 v[190:191], v[226:227], v[64:65]
	s_waitcnt lgkmcnt(2)
	v_mfma_f32_32x32x16_bf16 v[32:47], v[200:203], v[80:83], v[32:47]
	v_cvt_pk_bf16_f32 v64, v131, v135
	v_cvt_pk_bf16_f32 v65, v165, v209
	s_waitcnt lgkmcnt(0)
	v_mfma_f32_32x32x16_bf16 v[80:95], v[84:87], v[108:111], 0
	v_mfma_f32_32x32x16_bf16 v[80:95], v[204:207], v[104:107], v[80:95]
	v_exp_f32_e32 v189, v72
	v_exp_f32_e32 v187, v73
	v_exp_f32_e32 v185, v74
	v_exp_f32_e32 v183, v75
	v_exp_f32_e32 v181, v76
	v_exp_f32_e32 v177, v77
	v_exp_f32_e32 v175, v78
	v_exp_f32_e32 v173, v79
	v_cvt_pk_bf16_f32 v68, v189, v187
	v_cvt_pk_bf16_f32 v69, v185, v183
	v_cvt_pk_bf16_f32 v70, v181, v177
	v_cvt_pk_bf16_f32 v71, v175, v173
	s_waitcnt vmcnt(1)
	ds_write_b128 v166, v[120:123]
	s_waitcnt vmcnt(0)
	ds_write_b128 v167, v[124:127]
	global_load_dwordx4 v[128:131], v[128:129], off offset:1536
	s_nop 0
	global_load_dwordx4 v[132:135], v[132:133], off offset:1536
	v_mfma_f32_32x32x16_bf16 v[16:31], v[116:119], v[64:67], v[16:31]
	ds_read_b128 v[72:75], v160 offset:9280
	ds_read_b128 v[112:115], v160 offset:9312
	v_exp_f32_e32 v164, v80
	v_exp_f32_e32 v226, v81
	v_exp_f32_e32 v228, v82
	v_exp_f32_e32 v230, v83
	v_exp_f32_e32 v232, v84
	v_exp_f32_e32 v234, v85
	v_mfma_f32_32x32x16_bf16 v[0:15], v[192:195], v[64:67], v[0:15]
	v_exp_f32_e32 v236, v86
	v_cvt_pk_bf16_f32 v80, v164, v226
	v_cvt_pk_bf16_f32 v81, v228, v230
	v_cvt_pk_bf16_f32 v82, v232, v234
	v_mfma_f32_32x32x16_bf16 v[16:31], v[196:199], v[68:71], v[16:31]
	v_mfma_f32_32x32x16_bf16 v[0:15], v[200:203], v[68:71], v[0:15]
	v_exp_f32_e32 v200, v87
	s_nop 0
	v_cvt_pk_bf16_f32 v83, v236, v200
	s_waitcnt lgkmcnt(0)
	v_mfma_f32_32x32x16_bf16 v[64:79], v[72:75], v[100:103], 0
	v_mfma_f32_32x32x16_bf16 v[64:79], v[112:115], v[96:99], v[64:79]
	ds_read_b64_tr_b16 v[112:113], v147 offset:49152
	ds_read_b64_tr_b16 v[114:115], v147 offset:50688
	ds_read_b64_tr_b16 v[118:119], v147 offset:50752
	ds_read_b64_tr_b16 v[116:117], v147 offset:49216
	ds_read_b64_tr_b16 v[120:121], v147 offset:52224
	ds_read_b64_tr_b16 v[122:123], v147 offset:53760
	ds_read_b64_tr_b16 v[126:127], v147 offset:53824
	ds_read_b64_tr_b16 v[124:125], v147 offset:52288
	v_exp_f32_e32 v208, v88
	v_exp_f32_e32 v206, v89
	v_exp_f32_e32 v204, v90
	v_exp_f32_e32 v202, v91
	v_exp_f32_e32 v198, v92
	v_exp_f32_e32 v196, v93
	v_exp_f32_e32 v194, v94
	v_exp_f32_e32 v192, v95
	v_cvt_pk_bf16_f32 v84, v208, v206
	v_cvt_pk_bf16_f32 v85, v204, v202
	v_cvt_pk_bf16_f32 v86, v198, v196
	v_cvt_pk_bf16_f32 v87, v194, v192
	s_waitcnt lgkmcnt(6)
	v_mfma_f32_32x32x16_bf16 v[48:63], v[112:115], v[80:83], v[48:63]
	v_exp_f32_e32 v165, v64
	v_exp_f32_e32 v227, v65
	v_exp_f32_e32 v229, v66
	v_exp_f32_e32 v231, v67
	v_exp_f32_e32 v233, v68
	ds_read_b128 v[88:91], v160 offset:13824
	ds_read_b128 v[222:225], v160 offset:13856
	s_waitcnt lgkmcnt(6)
	v_mfma_f32_32x32x16_bf16 v[32:47], v[116:119], v[80:83], v[32:47]
	v_exp_f32_e32 v235, v69
	v_pk_add_f32 v[64:65], v[226:227], v[164:165]
	v_exp_f32_e32 v237, v70
	v_pk_add_f32 v[64:65], v[228:229], v[64:65]
	v_exp_f32_e32 v201, v71
	v_pk_add_f32 v[64:65], v[230:231], v[64:65]
	v_cvt_pk_bf16_f32 v66, v233, v235
	s_waitcnt lgkmcnt(4)
	v_mfma_f32_32x32x16_bf16 v[48:63], v[120:123], v[84:87], v[48:63]
	v_pk_add_f32 v[64:65], v[232:233], v[64:65]
	v_cvt_pk_bf16_f32 v67, v237, v201
	v_pk_add_f32 v[64:65], v[234:235], v[64:65]
	v_pk_add_f32 v[210:211], v[236:237], v[64:65]
	v_cvt_pk_bf16_f32 v64, v165, v227
	v_cvt_pk_bf16_f32 v65, v229, v231
	s_waitcnt lgkmcnt(1)
	v_mfma_f32_32x32x16_bf16 v[32:47], v[124:127], v[84:87], v[32:47]
	v_mfma_f32_32x32x16_bf16 v[80:95], v[88:91], v[108:111], 0
	s_waitcnt lgkmcnt(0)
	v_mfma_f32_32x32x16_bf16 v[80:95], v[222:225], v[104:107], v[80:95]
	v_exp_f32_e32 v209, v72
	v_exp_f32_e32 v207, v73
	v_exp_f32_e32 v205, v74
	v_exp_f32_e32 v203, v75
	v_exp_f32_e32 v199, v76
	v_exp_f32_e32 v197, v77
	v_exp_f32_e32 v195, v78
	v_exp_f32_e32 v193, v79
	v_cvt_pk_bf16_f32 v68, v209, v207
	v_cvt_pk_bf16_f32 v69, v205, v203
	v_cvt_pk_bf16_f32 v70, v199, v197
	v_cvt_pk_bf16_f32 v71, v195, v193
	v_mfma_f32_32x32x16_bf16 v[16:31], v[112:115], v[64:67], v[16:31]
	ds_read_b128 v[72:75], v160 offset:13888
	ds_read_b128 v[222:225], v160 offset:13920
	v_exp_f32_e32 v164, v80
	v_exp_f32_e32 v226, v81
	v_exp_f32_e32 v228, v82
	v_exp_f32_e32 v230, v83
	v_exp_f32_e32 v232, v84
	v_exp_f32_e32 v234, v85
	v_mfma_f32_32x32x16_bf16 v[0:15], v[116:119], v[64:67], v[0:15]
	v_exp_f32_e32 v236, v86
	v_exp_f32_e32 v238, v87
	v_cvt_pk_bf16_f32 v80, v164, v226
	v_cvt_pk_bf16_f32 v81, v228, v230
	v_cvt_pk_bf16_f32 v82, v232, v234
	v_cvt_pk_bf16_f32 v83, v236, v238
	v_mfma_f32_32x32x16_bf16 v[16:31], v[120:123], v[68:71], v[16:31]
	v_mfma_f32_32x32x16_bf16 v[0:15], v[124:127], v[68:71], v[0:15]
	s_waitcnt lgkmcnt(0)
; DI void diff_mfma_phase(const Args& A, int wave_s, int l, bool need_ctx, LAS unsigned char* lds) {
;     ...
;             for (int g = 0; g < 8; ++g) {
;                 const int c = g & 1, sub = g >> 1;
;                 bf16x8 kB0, kB1; f32x16 Sn;
;                 if (g < 7) { LAS unsigned char* kp = kl + (32 * ((g + 1) >> 1)) * KV_PITCH + (c ^ 1) * 64; kB0 = *(LAS bf16x8*)(kp); kB1 = *(LAS bf16x8*)(kp + 32); }
;                 if (c == 0) { O[1][0] = MFMA32(Vs[0], Pp0, O[1][0]); O[1][1] = MFMA32(Vs[2], Pp0, O[1][1]); O[1][0] = MFMA32(Vs[1], Pp1, O[1][0]); O[1][1] = MFMA32(Vs[3], Pp1, O[1][1]); }
;                 else        { O[0][0] = MFMA32(Vs[0], Pp0, O[0][0]); O[0][1] = MFMA32(Vs[2], Pp0, O[0][1]); O[0][0] = MFMA32(Vs[1], Pp1, O[0][0]); O[0][1] = MFMA32(Vs[3], Pp1, O[0][1]); }
;                 float t = 0.f;
; #pragma unroll
;                 for (int i = 0; i < 8; ++i) { Sc[i] = __builtin_amdgcn_exp2f(Sc[i]); t += Sc[i]; }
;                 const bf16x8 Pn0 = PACK8(Sc, 0);
;                 __builtin_amdgcn_sched_barrier(0);
;                 if (g < 7) { Sn = MFMA32(kB0, Qf[c ^ 1][0], negM); Sn = MFMA32(kB1, Qf[c ^ 1][1], Sn); }
;                 __builtin_amdgcn_sched_barrier(0);
;                 if (c == 0) { LAS unsigned char* vp = Vb + (32 * sub) * VP + voff; Vs[0] = tr_pairV(vp); Vs[1] = tr_pairV(vp + 16 * VP); Vs[2] = tr_pairV(vp + 64); Vs[3] = tr_pairV(vp + 16 * VP + 64); }
; #pragma unroll
;                 for (int i = 8; i < 16; ++i) { Sc[i] = __builtin_amdgcn_exp2f(Sc[i]); t += Sc[i]; }
;                 if (c == 0) ls0 += t; else ls1 += t;
;                 Pp0 = Pn0; Pp1 = PACK8(Sc, 1);
;                 if (g < 7) Sc = Sn;
;                 __builtin_amdgcn_sched_barrier(0);
;                 if (g == 3 && it + 1 < ntiles) {
;                     LAS unsigned char* kb2 = lds + (cur ^ 1) * DT_IMG;
;                     *(LAS v4u*)(kb2 + srow * KV_PITCH + sch * 16) = kreg[0]; *(LAS v4u*)(kb2 + (srow + 64) * KV_PITCH + sch * 16) = kreg[1];
;                     const int kr0 = (it + 1 < 64 ? kbase0 : kbase1) + (it + 1) * DT_ROWS;
;                     const char* vb_ = (const char*)(C.P + (size_t)kr0 * INW + CC_V + hd * 64);
;                     kreg[0] = *(const v4u*)(vb_ + sgoff); kreg[1] = *(const v4u*)(vb_ + (size_t)64 * INW * 2 + sgoff);
;                     __builtin_amdgcn_sched_barrier(0);
;                 }
;             }
	v_mfma_f32_32x32x16_bf16 v[64:79], v[72:75], v[100:103], 0
	v_mfma_f32_32x32x16_bf16 v[64:79], v[222:225], v[96:99], v[64:79]
	ds_read_b64_tr_b16 v[120:121], v147 offset:55296
	ds_read_b64_tr_b16 v[122:123], v147 offset:56832
	ds_read_b64_tr_b16 v[126:127], v147 offset:56896
	ds_read_b64_tr_b16 v[124:125], v147 offset:55360
	ds_read_b64_tr_b16 v[116:117], v147 offset:58368
	ds_read_b64_tr_b16 v[118:119], v147 offset:59904
	ds_read_b64_tr_b16 v[114:115], v147 offset:59968
	ds_read_b64_tr_b16 v[112:113], v147 offset:58432
	v_exp_f32_e32 v222, v88
	v_exp_f32_e32 v224, v89
	v_exp_f32_e32 v240, v90
	v_exp_f32_e32 v242, v91
	v_exp_f32_e32 v244, v92
	v_exp_f32_e32 v246, v93
	v_exp_f32_e32 v250, v94
	v_exp_f32_e32 v166, v95
	v_cvt_pk_bf16_f32 v84, v222, v224
	v_cvt_pk_bf16_f32 v85, v240, v242
	v_cvt_pk_bf16_f32 v86, v244, v246
	v_cvt_pk_bf16_f32 v87, v250, v166
	s_waitcnt lgkmcnt(6)
	v_mfma_f32_32x32x16_bf16 v[48:63], v[120:123], v[80:83], v[48:63]
	v_exp_f32_e32 v165, v64
	v_exp_f32_e32 v227, v65
	v_exp_f32_e32 v229, v66
	v_exp_f32_e32 v231, v67
	v_exp_f32_e32 v233, v68
	v_exp_f32_e32 v235, v69
	s_waitcnt lgkmcnt(4)
	v_mfma_f32_32x32x16_bf16 v[32:47], v[124:127], v[80:83], v[32:47]
	v_exp_f32_e32 v237, v70
	v_exp_f32_e32 v239, v71
	v_pk_add_f32 v[64:65], v[226:227], v[164:165]
	v_cvt_pk_bf16_f32 v88, v165, v227
	v_pk_add_f32 v[64:65], v[228:229], v[64:65]
	v_cvt_pk_bf16_f32 v89, v229, v231
	v_pk_add_f32 v[64:65], v[230:231], v[64:65]
	s_waitcnt lgkmcnt(2)
	v_mfma_f32_32x32x16_bf16 v[48:63], v[116:119], v[84:87], v[48:63]
	v_pk_add_f32 v[64:65], v[232:233], v[64:65]
	v_cvt_pk_bf16_f32 v90, v233, v235
	v_cvt_pk_bf16_f32 v91, v237, v239
	v_pk_add_f32 v[64:65], v[234:235], v[64:65]
	s_waitcnt lgkmcnt(0)
	v_mfma_f32_32x32x16_bf16 v[32:47], v[112:115], v[84:87], v[32:47]
	v_exp_f32_e32 v223, v72
	v_exp_f32_e32 v225, v73
	v_exp_f32_e32 v241, v74
	v_pk_add_f32 v[66:67], v[170:171], v[178:179]
	v_pk_add_f32 v[68:69], v[188:189], v[190:191]
	v_pk_add_f32 v[70:71], v[200:201], v[210:211]
	v_pk_add_f32 v[64:65], v[236:237], v[64:65]
	v_exp_f32_e32 v243, v75
	v_pk_add_f32 v[66:67], v[168:169], v[66:67]
	v_pk_add_f32 v[68:69], v[186:187], v[68:69]
	v_pk_add_f32 v[70:71], v[208:209], v[70:71]
	v_pk_add_f32 v[64:65], v[238:239], v[64:65]
	v_exp_f32_e32 v245, v76
	v_pk_add_f32 v[66:67], v[158:159], v[66:67]
	v_pk_add_f32 v[68:69], v[184:185], v[68:69]
	v_pk_add_f32 v[70:71], v[206:207], v[70:71]
	v_pk_add_f32 v[64:65], v[222:223], v[64:65]
	v_exp_f32_e32 v247, v77
	v_pk_add_f32 v[66:67], v[156:157], v[66:67]
	v_pk_add_f32 v[68:69], v[182:183], v[68:69]
	v_pk_add_f32 v[70:71], v[204:205], v[70:71]
	v_pk_add_f32 v[64:65], v[224:225], v[64:65]
	v_exp_f32_e32 v251, v78
	v_pk_add_f32 v[66:67], v[154:155], v[66:67]
	v_pk_add_f32 v[68:69], v[180:181], v[68:69]
	v_pk_add_f32 v[70:71], v[202:203], v[70:71]
	v_pk_add_f32 v[64:65], v[240:241], v[64:65]
	v_exp_f32_e32 v167, v79
	v_pk_add_f32 v[66:67], v[152:153], v[66:67]
	v_pk_add_f32 v[68:69], v[176:177], v[68:69]
	v_pk_add_f32 v[70:71], v[198:199], v[70:71]
	v_pk_add_f32 v[64:65], v[242:243], v[64:65]
	v_pk_add_f32 v[66:67], v[150:151], v[66:67]
	v_pk_add_f32 v[68:69], v[174:175], v[68:69]
	v_pk_add_f32 v[70:71], v[196:197], v[70:71]
	v_pk_add_f32 v[64:65], v[244:245], v[64:65]
	v_pk_add_f32 v[66:67], v[148:149], v[66:67]
	v_pk_add_f32 v[68:69], v[172:173], v[68:69]
	v_pk_add_f32 v[70:71], v[194:195], v[70:71]
	v_pk_add_f32 v[64:65], v[246:247], v[64:65]
	v_pk_add_f32 v[66:67], v[66:67], v[68:69]
	v_pk_add_f32 v[68:69], v[192:193], v[70:71]
	v_pk_add_f32 v[64:65], v[250:251], v[64:65]
	v_pk_add_f32 v[66:67], v[66:67], v[68:69]
	v_pk_add_f32 v[64:65], v[166:167], v[64:65]
	v_cvt_pk_bf16_f32 v92, v223, v225
	v_cvt_pk_bf16_f32 v93, v241, v243
	v_cvt_pk_bf16_f32 v94, v245, v247
	v_cvt_pk_bf16_f32 v95, v251, v167
	v_pk_add_f32 v[148:149], v[66:67], v[64:65]
	s_mulk_i32 s15, 0x6000
	s_add_i32 s15, s15, 0
	s_add_u32 s6, s6, 0x80
	s_addc_u32 s7, s7, 0
	v_add3_u32 v64, s15, v217, v212
	v_add3_u32 v65, s15, v216, v212
	s_cmp_eq_u32 s13, s14
	s_mov_b32 s15, s14
	s_waitcnt vmcnt(1)
	ds_write_b128 v65, v[128:131] offset:36864
	s_waitcnt vmcnt(0)
	ds_write_b128 v64, v[132:135] offset:36864
	s_waitcnt lgkmcnt(0)
	s_barrier
	s_cbranch_scc0 .LBB0_406
; DI void diff_mfma_phase(const Args& A, int wave_s, int l, bool need_ctx, LAS unsigned char* lds) {
;     ...
;         for (int it = 0; it < ntiles; ++it) {
;             const int cur = it & 1;
;             if (it + 1 < ntiles) { const int kr0 = (it + 1 < 64 ? kbase0 : kbase1) + (it + 1) * DT_ROWS;
;                 const char* kb_ = (const char*)(C.P + (size_t)kr0 * INW + CC_K + hd * 64);
;                 kreg[0] = *(const v4u*)(kb_ + sgoff); kreg[1] = *(const v4u*)(kb_ + (size_t)64 * INW * 2 + sgoff); }
;             LAS unsigned char* Kb = lds + cur * DT_IMG; LAS unsigned char* Vb = lds + VOFF0 + cur * DV_IMG;
;             LAS unsigned char* kl = Kb + r * KV_PITCH + h * 16;
;             f32x16 Sc;
;             { const bf16x8 kA0 = *(LAS bf16x8*)(kl), kA1 = *(LAS bf16x8*)(kl + 32); Sc = MFMA32(kA0, Qf[0][0], negM); Sc = MFMA32(kA1, Qf[0][1], Sc); }
; #pragma unroll
;             for (int g = 0; g < 8; ++g) {
;                 const int c = g & 1, sub = g >> 1;
;                 bf16x8 kB0, kB1; f32x16 Sn;
;                 if (g < 7) { LAS unsigned char* kp = kl + (32 * ((g + 1) >> 1)) * KV_PITCH + (c ^ 1) * 64; kB0 = *(LAS bf16x8*)(kp); kB1 = *(LAS bf16x8*)(kp + 32); }
;                 if (c == 0) { O[1][0] = MFMA32(Vs[0], Pp0, O[1][0]); O[1][1] = MFMA32(Vs[2], Pp0, O[1][1]); O[1][0] = MFMA32(Vs[1], Pp1, O[1][0]); O[1][1] = MFMA32(Vs[3], Pp1, O[1][1]); }
;                 else        { O[0][0] = MFMA32(Vs[0], Pp0, O[0][0]); O[0][1] = MFMA32(Vs[2], Pp0, O[0][1]); O[0][0] = MFMA32(Vs[1], Pp1, O[0][0]); O[0][1] = MFMA32(Vs[3], Pp1, O[0][1]); }
;                 float t = 0.f;
; #pragma unroll
;                 for (int i = 0; i < 8; ++i) { Sc[i] = __builtin_amdgcn_exp2f(Sc[i]); t += Sc[i]; }
;                 const bf16x8 Pn0 = PACK8(Sc, 0);
;                 __builtin_amdgcn_sched_barrier(0);
;                 if (g < 7) { Sn = MFMA32(kB0, Qf[c ^ 1][0], negM); Sn = MFMA32(kB1, Qf[c ^ 1][1], Sn); }
;                 __builtin_amdgcn_sched_barrier(0);
;                 if (c == 0) { LAS unsigned char* vp = Vb + (32 * sub) * VP + voff; Vs[0] = tr_pairV(vp); Vs[1] = tr_pairV(vp + 16 * VP); Vs[2] = tr_pairV(vp + 64); Vs[3] = tr_pairV(vp + 16 * VP + 64); }
; #pragma unroll
;                 for (int i = 8; i < 16; ++i) { Sc[i] = __builtin_amdgcn_exp2f(Sc[i]); t += Sc[i]; }
;                 if (c == 0) ls0 += t; else ls1 += t;
	s_and_b32 s6, s13, 1
	s_mul_i32 s7, s6, 0x4800
	v_add_u32_e32 v135, s7, v218
	ds_read_b128 v[64:67], v135
	v_mfma_f32_32x32x16_bf16 v[16:31], v[120:123], v[88:91], v[16:31]
	s_mulk_i32 s6, 0x6000
	v_add_u32_e32 v134, s6, v219
	s_waitcnt lgkmcnt(0)
	v_mfma_f32_32x32x16_bf16 v[72:87], v[64:67], v[108:111], 0
	ds_read_b128 v[64:67], v135 offset:32
	v_mfma_f32_32x32x16_bf16 v[0:15], v[124:127], v[88:91], v[0:15]
	s_waitcnt lgkmcnt(0)
	v_mfma_f32_32x32x16_bf16 v[72:87], v[64:67], v[104:107], v[72:87]
	ds_read_b128 v[64:67], v135 offset:64
	ds_read_b128 v[88:91], v135 offset:96
	v_mfma_f32_32x32x16_bf16 v[16:31], v[116:119], v[92:95], v[16:31]
	s_nop 8
	v_exp_f32_e32 v68, v72
	v_exp_f32_e32 v158, v73
	v_exp_f32_e32 v164, v74
	v_exp_f32_e32 v176, v75
	v_exp_f32_e32 v178, v76
	v_exp_f32_e32 v180, v77
	v_exp_f32_e32 v182, v78
	v_exp_f32_e32 v184, v79
	v_add_f32_e32 v160, 0, v68
	v_cvt_pk_bf16_f32 v116, v68, v158
	v_cvt_pk_bf16_f32 v117, v164, v176
	v_cvt_pk_bf16_f32 v118, v178, v180
	v_cvt_pk_bf16_f32 v119, v182, v184
	v_mfma_f32_32x32x16_bf16 v[0:15], v[112:115], v[92:95], v[0:15]
	s_waitcnt lgkmcnt(0)
	v_mfma_f32_32x32x16_bf16 v[64:79], v[64:67], v[100:103], 0
	v_mfma_f32_32x32x16_bf16 v[64:79], v[88:91], v[96:99], v[64:79]
	ds_read_b64_tr_b16 v[150:151], v134 offset:36864
	ds_read_b64_tr_b16 v[152:153], v134 offset:38400
	ds_read_b64_tr_b16 v[156:157], v134 offset:38464
	ds_read_b64_tr_b16 v[154:155], v134 offset:36928
	ds_read_b64_tr_b16 v[168:169], v134 offset:39936
	ds_read_b64_tr_b16 v[170:171], v134 offset:41472
	ds_read_b64_tr_b16 v[174:175], v134 offset:41536
	ds_read_b64_tr_b16 v[172:173], v134 offset:40000
	v_exp_f32_e32 v112, v80
	v_exp_f32_e32 v186, v81
	v_exp_f32_e32 v188, v82
	v_exp_f32_e32 v190, v83
	v_exp_f32_e32 v192, v84
	v_exp_f32_e32 v194, v85
	v_exp_f32_e32 v196, v86
	v_exp_f32_e32 v198, v87
	v_cvt_pk_bf16_f32 v80, v112, v186
	v_cvt_pk_bf16_f32 v81, v188, v190
	v_cvt_pk_bf16_f32 v82, v192, v194
	v_cvt_pk_bf16_f32 v83, v196, v198
	s_waitcnt lgkmcnt(6)
	v_mfma_f32_32x32x16_bf16 v[48:63], v[150:153], v[116:119], v[48:63]
	ds_read_b128 v[84:87], v135 offset:4608
	ds_read_b128 v[120:123], v135 offset:4640
	v_exp_f32_e32 v64, v64
	v_exp_f32_e32 v202, v65
	v_exp_f32_e32 v204, v66
	v_exp_f32_e32 v206, v67
	v_exp_f32_e32 v208, v68
	v_exp_f32_e32 v132, v69
	s_waitcnt lgkmcnt(6)
	v_mfma_f32_32x32x16_bf16 v[32:47], v[154:157], v[116:119], v[32:47]
	v_exp_f32_e32 v130, v70
	v_exp_f32_e32 v114, v71
	v_add_f32_e32 v200, 0, v64
	v_cvt_pk_bf16_f32 v64, v64, v202
	v_cvt_pk_bf16_f32 v65, v204, v206
	v_cvt_pk_bf16_f32 v66, v208, v132
	v_cvt_pk_bf16_f32 v67, v130, v114
	s_waitcnt lgkmcnt(2)
	v_mfma_f32_32x32x16_bf16 v[48:63], v[168:171], v[80:83], v[48:63]
	v_mfma_f32_32x32x16_bf16 v[32:47], v[172:175], v[80:83], v[32:47]
	s_waitcnt lgkmcnt(0)
	v_mfma_f32_32x32x16_bf16 v[80:95], v[84:87], v[108:111], 0
	v_mfma_f32_32x32x16_bf16 v[80:95], v[120:123], v[104:107], v[80:95]
	v_exp_f32_e32 v210, v72
	v_exp_f32_e32 v116, v73
	v_exp_f32_e32 v120, v74
	v_exp_f32_e32 v118, v75
	v_exp_f32_e32 v124, v76
	v_exp_f32_e32 v122, v77
	v_exp_f32_e32 v128, v78
	v_exp_f32_e32 v126, v79
	v_cvt_pk_bf16_f32 v68, v210, v116
	v_cvt_pk_bf16_f32 v69, v120, v118
	v_cvt_pk_bf16_f32 v70, v124, v122
	v_cvt_pk_bf16_f32 v71, v128, v126
	v_mfma_f32_32x32x16_bf16 v[16:31], v[150:153], v[64:67], v[16:31]
	v_exp_f32_e32 v159, v80
	v_exp_f32_e32 v165, v81
	ds_read_b128 v[72:75], v135 offset:4672
	ds_read_b128 v[150:153], v135 offset:4704
	v_exp_f32_e32 v177, v82
	v_exp_f32_e32 v179, v83
	v_exp_f32_e32 v181, v84
	v_exp_f32_e32 v183, v85
	v_mfma_f32_32x32x16_bf16 v[0:15], v[154:157], v[64:67], v[0:15]
	v_exp_f32_e32 v185, v86
	v_exp_f32_e32 v113, v87
	v_pk_add_f32 v[64:65], v[158:159], v[160:161]
	v_cvt_pk_bf16_f32 v80, v159, v165
	v_pk_add_f32 v[64:65], v[164:165], v[64:65]
	v_cvt_pk_bf16_f32 v81, v177, v179
	v_pk_add_f32 v[64:65], v[176:177], v[64:65]
	v_mfma_f32_32x32x16_bf16 v[16:31], v[168:171], v[68:71], v[16:31]
	v_add_f32_e64 v222, v178, v64
	v_add_f32_e64 v223, v179, v65
	v_cvt_pk_bf16_f32 v82, v181, v183
	v_cvt_pk_bf16_f32 v83, v185, v113
	v_mfma_f32_32x32x16_bf16 v[0:15], v[172:175], v[68:71], v[0:15]
	s_waitcnt lgkmcnt(0)
	v_mfma_f32_32x32x16_bf16 v[64:79], v[72:75], v[100:103], 0
	v_mfma_f32_32x32x16_bf16 v[64:79], v[150:153], v[96:99], v[64:79]
	ds_read_b64_tr_b16 v[150:151], v134 offset:43008
	ds_read_b64_tr_b16 v[152:153], v134 offset:44544
	ds_read_b64_tr_b16 v[156:157], v134 offset:44608
	ds_read_b64_tr_b16 v[154:155], v134 offset:43072
	ds_read_b64_tr_b16 v[168:169], v134 offset:46080
	ds_read_b64_tr_b16 v[170:171], v134 offset:47616
	ds_read_b64_tr_b16 v[174:175], v134 offset:47680
	ds_read_b64_tr_b16 v[172:173], v134 offset:46144
	v_exp_f32_e32 v187, v88
	v_pk_add_f32 v[84:85], v[180:181], v[222:223]
	v_exp_f32_e32 v189, v89
	v_pk_add_f32 v[84:85], v[182:183], v[84:85]
	v_exp_f32_e32 v191, v90
	v_pk_add_f32 v[84:85], v[184:185], v[84:85]
	v_exp_f32_e32 v193, v91
	v_pk_add_f32 v[84:85], v[112:113], v[84:85]
	v_exp_f32_e32 v195, v92
	v_pk_add_f32 v[84:85], v[186:187], v[84:85]
	v_exp_f32_e32 v197, v93
	v_pk_add_f32 v[84:85], v[188:189], v[84:85]
	v_exp_f32_e32 v199, v94
	v_pk_add_f32 v[84:85], v[190:191], v[84:85]
	v_exp_f32_e32 v87, v95
	v_pk_add_f32 v[84:85], v[192:193], v[84:85]
	v_mov_b32_e32 v86, v148
	v_pk_add_f32 v[84:85], v[194:195], v[84:85]
	s_nop 0
	v_pk_add_f32 v[84:85], v[196:197], v[84:85]
	s_nop 0
	v_pk_add_f32 v[84:85], v[198:199], v[84:85]
	s_nop 0
	v_pk_add_f32 v[112:113], v[86:87], v[84:85]
	v_cvt_pk_bf16_f32 v84, v187, v189
	v_cvt_pk_bf16_f32 v85, v191, v193
	v_cvt_pk_bf16_f32 v86, v195, v197
	v_cvt_pk_bf16_f32 v87, v199, v87
	s_waitcnt lgkmcnt(6)
; DI void diff_mfma_phase(const Args& A, int wave_s, int l, bool need_ctx, LAS unsigned char* lds) {
;     ...
;             { const bf16x8 kA0 = *(LAS bf16x8*)(kl), kA1 = *(LAS bf16x8*)(kl + 32); Sc = MFMA32(kA0, Qf[0][0], negM); Sc = MFMA32(kA1, Qf[0][1], Sc); }
; #pragma unroll
;             for (int g = 0; g < 8; ++g) {
;                 const int c = g & 1, sub = g >> 1;
;                 bf16x8 kB0, kB1; f32x16 Sn;
;                 if (g < 7) { LAS unsigned char* kp = kl + (32 * ((g + 1) >> 1)) * KV_PITCH + (c ^ 1) * 64; kB0 = *(LAS bf16x8*)(kp); kB1 = *(LAS bf16x8*)(kp + 32); }
;                 if (c == 0) { O[1][0] = MFMA32(Vs[0], Pp0, O[1][0]); O[1][1] = MFMA32(Vs[2], Pp0, O[1][1]); O[1][0] = MFMA32(Vs[1], Pp1, O[1][0]); O[1][1] = MFMA32(Vs[3], Pp1, O[1][1]); }
;                 else        { O[0][0] = MFMA32(Vs[0], Pp0, O[0][0]); O[0][1] = MFMA32(Vs[2], Pp0, O[0][1]); O[0][0] = MFMA32(Vs[1], Pp1, O[0][0]); O[0][1] = MFMA32(Vs[3], Pp1, O[0][1]); }
;                 float t = 0.f;
; #pragma unroll
;                 for (int i = 0; i < 8; ++i) { Sc[i] = __builtin_amdgcn_exp2f(Sc[i]); t += Sc[i]; }
;                 const bf16x8 Pn0 = PACK8(Sc, 0);
;                 __builtin_amdgcn_sched_barrier(0);
;                 if (g < 7) { Sn = MFMA32(kB0, Qf[c ^ 1][0], negM); Sn = MFMA32(kB1, Qf[c ^ 1][1], Sn); }
;                 __builtin_amdgcn_sched_barrier(0);
;                 if (c == 0) { LAS unsigned char* vp = Vb + (32 * sub) * VP + voff; Vs[0] = tr_pairV(vp); Vs[1] = tr_pairV(vp + 16 * VP); Vs[2] = tr_pairV(vp + 64); Vs[3] = tr_pairV(vp + 16 * VP + 64); }
; #pragma unroll
;                 for (int i = 8; i < 16; ++i) { Sc[i] = __builtin_amdgcn_exp2f(Sc[i]); t += Sc[i]; }
;                 if (c == 0) ls0 += t; else ls1 += t;
;                 Pp0 = Pn0; Pp1 = PACK8(Sc, 1);
;                 if (g < 7) Sc = Sn;
;                 __builtin_amdgcn_sched_barrier(0);
;                 if (g == 3 && it + 1 < ntiles) {
;                     LAS unsigned char* kb2 = lds + (cur ^ 1) * DT_IMG;
;                     *(LAS v4u*)(kb2 + srow * KV_PITCH + sch * 16) = kreg[0]; *(LAS v4u*)(kb2 + (srow + 64) * KV_PITCH + sch * 16) = kreg[1];
;                     const int kr0 = (it + 1 < 64 ? kbase0 : kbase1) + (it + 1) * DT_ROWS;
;                     const char* vb_ = (const char*)(C.P + (size_t)kr0 * INW + CC_V + hd * 64);
	v_mfma_f32_32x32x16_bf16 v[48:63], v[150:153], v[80:83], v[48:63]
	v_exp_f32_e32 v203, v64
	v_exp_f32_e32 v205, v65
	ds_read_b128 v[88:91], v135 offset:9216
	ds_read_b128 v[176:179], v135 offset:9248
	v_exp_f32_e32 v207, v66
	v_exp_f32_e32 v209, v67
	v_mov_b32_e32 v201, v161
	v_exp_f32_e32 v133, v68
	s_waitcnt lgkmcnt(6)
	v_mfma_f32_32x32x16_bf16 v[32:47], v[154:157], v[80:83], v[32:47]
	v_exp_f32_e32 v131, v69
	v_exp_f32_e32 v115, v70
	v_exp_f32_e32 v211, v71
	v_pk_add_f32 v[64:65], v[202:203], v[200:201]
	v_cvt_pk_bf16_f32 v66, v133, v131
	v_pk_add_f32 v[64:65], v[204:205], v[64:65]
	v_cvt_pk_bf16_f32 v67, v115, v211
	v_pk_add_f32 v[64:65], v[206:207], v[64:65]
	s_waitcnt lgkmcnt(4)
	v_mfma_f32_32x32x16_bf16 v[48:63], v[168:171], v[84:87], v[48:63]
	v_add_f32_e64 v158, v208, v64
	v_add_f32_e64 v159, v209, v65
	v_cvt_pk_bf16_f32 v64, v203, v205
	v_cvt_pk_bf16_f32 v65, v207, v209
	s_waitcnt lgkmcnt(1)
	v_mfma_f32_32x32x16_bf16 v[32:47], v[172:175], v[84:87], v[32:47]
	v_mfma_f32_32x32x16_bf16 v[80:95], v[88:91], v[108:111], 0
	s_waitcnt lgkmcnt(0)
	v_mfma_f32_32x32x16_bf16 v[80:95], v[176:179], v[104:107], v[80:95]
	v_exp_f32_e32 v117, v72
	v_pk_add_f32 v[68:69], v[132:133], v[158:159]
	v_exp_f32_e32 v121, v73
	v_pk_add_f32 v[68:69], v[130:131], v[68:69]
	v_exp_f32_e32 v119, v74
	v_pk_add_f32 v[68:69], v[114:115], v[68:69]
	v_exp_f32_e32 v125, v75
	v_pk_add_f32 v[68:69], v[210:211], v[68:69]
	v_exp_f32_e32 v123, v76
	v_pk_add_f32 v[68:69], v[116:117], v[68:69]
	v_exp_f32_e32 v129, v77
	v_pk_add_f32 v[68:69], v[120:121], v[68:69]
	v_exp_f32_e32 v127, v78
	v_pk_add_f32 v[68:69], v[118:119], v[68:69]
	v_exp_f32_e32 v71, v79
	v_pk_add_f32 v[68:69], v[124:125], v[68:69]
	v_mov_b32_e32 v70, v149
	v_pk_add_f32 v[68:69], v[122:123], v[68:69]
	s_nop 0
	v_pk_add_f32 v[68:69], v[128:129], v[68:69]
	s_nop 0
	v_pk_add_f32 v[68:69], v[126:127], v[68:69]
	s_nop 0
	v_pk_add_f32 v[114:115], v[70:71], v[68:69]
	v_cvt_pk_bf16_f32 v68, v117, v121
	v_cvt_pk_bf16_f32 v69, v119, v125
	v_cvt_pk_bf16_f32 v70, v123, v129
	v_cvt_pk_bf16_f32 v71, v127, v71
	v_mfma_f32_32x32x16_bf16 v[16:31], v[150:153], v[64:67], v[16:31]
	ds_read_b128 v[72:75], v135 offset:9280
	ds_read_b128 v[116:119], v135 offset:9312
	v_exp_f32_e32 v152, v81
	v_exp_f32_e32 v158, v84
	v_exp_f32_e32 v164, v85
	v_mfma_f32_32x32x16_bf16 v[0:15], v[154:157], v[64:67], v[0:15]
	v_exp_f32_e32 v64, v80
	v_exp_f32_e32 v154, v82
	v_exp_f32_e32 v156, v83
	v_cvt_pk_bf16_f32 v82, v158, v164
	v_add_f32_e32 v160, 0, v64
	v_cvt_pk_bf16_f32 v80, v64, v152
	v_cvt_pk_bf16_f32 v81, v154, v156
	v_mfma_f32_32x32x16_bf16 v[16:31], v[168:171], v[68:71], v[16:31]
	v_exp_f32_e32 v168, v86
	v_exp_f32_e32 v170, v87
	s_nop 0
	v_cvt_pk_bf16_f32 v83, v168, v170
	v_mfma_f32_32x32x16_bf16 v[0:15], v[172:175], v[68:71], v[0:15]
	s_waitcnt lgkmcnt(0)
	v_mfma_f32_32x32x16_bf16 v[64:79], v[72:75], v[100:103], 0
	v_mfma_f32_32x32x16_bf16 v[64:79], v[116:119], v[96:99], v[64:79]
	ds_read_b64_tr_b16 v[122:123], v134 offset:49152
	ds_read_b64_tr_b16 v[124:125], v134 offset:50688
	ds_read_b64_tr_b16 v[128:129], v134 offset:50752
	ds_read_b64_tr_b16 v[126:127], v134 offset:49216
	ds_read_b64_tr_b16 v[130:131], v134 offset:52224
	ds_read_b64_tr_b16 v[132:133], v134 offset:53760
	ds_read_b64_tr_b16 v[150:151], v134 offset:53824
	ds_read_b64_tr_b16 v[148:149], v134 offset:52288
	v_exp_f32_e32 v172, v88
	v_exp_f32_e32 v174, v89
	v_exp_f32_e32 v176, v90
	v_exp_f32_e32 v178, v91
	v_exp_f32_e32 v180, v92
	v_exp_f32_e32 v182, v93
	v_exp_f32_e32 v184, v94
	v_exp_f32_e32 v186, v95
	v_cvt_pk_bf16_f32 v84, v172, v174
	v_cvt_pk_bf16_f32 v85, v176, v178
	v_cvt_pk_bf16_f32 v86, v180, v182
	v_cvt_pk_bf16_f32 v87, v184, v186
	s_waitcnt lgkmcnt(6)
	v_mfma_f32_32x32x16_bf16 v[48:63], v[122:125], v[80:83], v[48:63]
	ds_read_b128 v[88:91], v135 offset:13824
	ds_read_b128 v[116:119], v135 offset:13856
	v_exp_f32_e32 v64, v64
	v_exp_f32_e32 v190, v65
	v_exp_f32_e32 v192, v66
	v_exp_f32_e32 v194, v67
	v_exp_f32_e32 v196, v68
	v_exp_f32_e32 v198, v69
	s_waitcnt lgkmcnt(6)
	v_mfma_f32_32x32x16_bf16 v[32:47], v[126:129], v[80:83], v[32:47]
	v_exp_f32_e32 v200, v70
	v_exp_f32_e32 v202, v71
	v_add_f32_e32 v188, 0, v64
	v_cvt_pk_bf16_f32 v64, v64, v190
	v_cvt_pk_bf16_f32 v65, v192, v194
	v_cvt_pk_bf16_f32 v66, v196, v198
	v_cvt_pk_bf16_f32 v67, v200, v202
	s_waitcnt lgkmcnt(2)
	v_mfma_f32_32x32x16_bf16 v[48:63], v[130:133], v[84:87], v[48:63]
	v_mfma_f32_32x32x16_bf16 v[32:47], v[148:151], v[84:87], v[32:47]
	s_waitcnt lgkmcnt(0)
	v_mfma_f32_32x32x16_bf16 v[80:95], v[88:91], v[108:111], 0
	v_mfma_f32_32x32x16_bf16 v[80:95], v[116:119], v[104:107], v[80:95]
	v_exp_f32_e32 v204, v72
	v_exp_f32_e32 v104, v73
	v_exp_f32_e32 v108, v74
	v_exp_f32_e32 v106, v75
	v_exp_f32_e32 v116, v76
	v_exp_f32_e32 v110, v77
	v_exp_f32_e32 v120, v78
	v_exp_f32_e32 v118, v79
	v_cvt_pk_bf16_f32 v68, v204, v104
	v_cvt_pk_bf16_f32 v69, v108, v106
	v_cvt_pk_bf16_f32 v70, v116, v110
	v_cvt_pk_bf16_f32 v71, v120, v118
	v_mfma_f32_32x32x16_bf16 v[16:31], v[122:125], v[64:67], v[16:31]
	v_exp_f32_e32 v153, v80
	v_exp_f32_e32 v155, v81
	ds_read_b128 v[72:75], v135 offset:13888
	ds_read_b128 v[122:125], v135 offset:13920
	v_exp_f32_e32 v157, v82
	v_exp_f32_e32 v159, v83
	v_exp_f32_e32 v165, v84
	v_exp_f32_e32 v169, v85
	v_mfma_f32_32x32x16_bf16 v[0:15], v[126:129], v[64:67], v[0:15]
	v_exp_f32_e32 v171, v86
	v_exp_f32_e32 v173, v87
	v_pk_add_f32 v[64:65], v[152:153], v[160:161]
	v_cvt_pk_bf16_f32 v80, v153, v155
	v_pk_add_f32 v[64:65], v[154:155], v[64:65]
	v_cvt_pk_bf16_f32 v81, v157, v159
	v_pk_add_f32 v[64:65], v[156:157], v[64:65]
	v_mfma_f32_32x32x16_bf16 v[16:31], v[130:133], v[68:71], v[16:31]
	v_add_f32_e64 v126, v158, v64
	v_add_f32_e64 v127, v159, v65
	v_cvt_pk_bf16_f32 v82, v165, v169
	v_cvt_pk_bf16_f32 v83, v171, v173
	v_mfma_f32_32x32x16_bf16 v[0:15], v[148:151], v[68:71], v[0:15]
	s_waitcnt lgkmcnt(0)
; #define LAS __attribute__((address_space(3)))
; DI float shx_(int lane, float v, int m) { return __builtin_bit_cast(float, __builtin_amdgcn_ds_bpermute((lane ^ m) << 2, __builtin_bit_cast(int, v))); }
; #define MFMA32(a, b, c) __builtin_amdgcn_mfma_f32_32x32x16_bf16((a), (b), (c), 0, 0, 0)
; DI void diff_mfma_phase(const Args& A, int wave_s, int l, bool need_ctx, LAS unsigned char* lds) {
;     ...
;             if (it + 1 < ntiles) { LAS unsigned char* vb2 = lds + VOFF0 + (cur ^ 1) * DV_IMG;
;                 *(LAS v4u*)(vb2 + srow * VP + sch * 16) = kreg[0]; *(LAS v4u*)(vb2 + (srow + 64) * VP + sch * 16) = kreg[1]; }
;             __syncthreads();
;         }
;         O[1][0] = MFMA32(Vs[0], Pp0, O[1][0]); O[1][1] = MFMA32(Vs[2], Pp0, O[1][1]); O[1][0] = MFMA32(Vs[1], Pp1, O[1][0]); O[1][1] = MFMA32(Vs[3], Pp1, O[1][1]);
;         ls0 += shx_(C.lane, ls0, 32); ls1 += shx_(C.lane, ls1, 32);
;         const float inv0 = 1.f / ls0, inv1 = lam / ls1;
;         float ss = 0.f;
; #pragma unroll
;         for (int mt = 0; mt < 2; ++mt)
; #pragma unroll
;             for (int i = 0; i < 16; ++i) { const float o = O[0][mt][i] * inv0 - O[1][mt][i] * inv1; O[0][mt][i] = o; ss += o * o; }
	v_mfma_f32_32x32x16_bf16 v[64:79], v[72:75], v[100:103], 0
	v_mfma_f32_32x32x16_bf16 v[64:79], v[122:125], v[96:99], v[64:79]
	v_exp_f32_e32 v175, v88
	v_exp_f32_e32 v177, v89
	v_pk_add_f32 v[88:89], v[164:165], v[126:127]
	ds_read_b64_tr_b16 v[84:85], v134 offset:55296
	ds_read_b64_tr_b16 v[86:87], v134 offset:56832
	ds_read_b64_tr_b16 v[98:99], v134 offset:56896
	ds_read_b64_tr_b16 v[96:97], v134 offset:55360
	ds_read_b64_tr_b16 v[100:101], v134 offset:58368
	ds_read_b64_tr_b16 v[102:103], v134 offset:59904
	ds_read_b64_tr_b16 v[124:125], v134 offset:59968
	ds_read_b64_tr_b16 v[122:123], v134 offset:58432
	v_pk_add_f32 v[88:89], v[168:169], v[88:89]
	v_exp_f32_e32 v179, v90
	v_pk_add_f32 v[88:89], v[170:171], v[88:89]
	v_exp_f32_e32 v181, v91
	v_pk_add_f32 v[88:89], v[172:173], v[88:89]
	v_exp_f32_e32 v183, v92
	v_pk_add_f32 v[88:89], v[174:175], v[88:89]
	v_exp_f32_e32 v185, v93
	v_pk_add_f32 v[88:89], v[176:177], v[88:89]
	v_exp_f32_e32 v187, v94
	v_exp_f32_e32 v92, v95
	v_pk_add_f32 v[88:89], v[178:179], v[88:89]
	v_pk_add_f32 v[90:91], v[112:113], v[112:113] op_sel:[0,1] op_sel_hi:[1,0]
	v_pk_add_f32 v[88:89], v[180:181], v[88:89]
	v_mov_b32_e32 v91, v92
	v_pk_add_f32 v[88:89], v[182:183], v[88:89]
	s_nop 0
	v_pk_add_f32 v[88:89], v[184:185], v[88:89]
	s_nop 0
	v_pk_add_f32 v[88:89], v[186:187], v[88:89]
	s_nop 0
	v_pk_add_f32 v[88:89], v[90:91], v[88:89]
	v_cvt_pk_bf16_f32 v90, v183, v185
	v_add_f32_e32 v93, v88, v89
	v_cvt_pk_bf16_f32 v88, v175, v177
	v_cvt_pk_bf16_f32 v89, v179, v181
	v_cvt_pk_bf16_f32 v91, v187, v92
	s_waitcnt lgkmcnt(6)
	v_mfma_f32_32x32x16_bf16 v[48:63], v[84:87], v[80:83], v[48:63]
	v_exp_f32_e32 v191, v64
	v_exp_f32_e32 v193, v65
	v_exp_f32_e32 v195, v66
	v_exp_f32_e32 v197, v67
	v_mov_b32_e32 v189, v161
	v_exp_f32_e32 v199, v68
	v_exp_f32_e32 v201, v69
	s_waitcnt lgkmcnt(4)
	v_mfma_f32_32x32x16_bf16 v[32:47], v[96:99], v[80:83], v[32:47]
	v_exp_f32_e32 v203, v70
	v_exp_f32_e32 v205, v71
	v_pk_add_f32 v[64:65], v[190:191], v[188:189]
	v_cvt_pk_bf16_f32 v66, v199, v201
	v_pk_add_f32 v[64:65], v[192:193], v[64:65]
	v_cvt_pk_bf16_f32 v67, v203, v205
	v_pk_add_f32 v[64:65], v[194:195], v[64:65]
	s_waitcnt lgkmcnt(2)
	v_mfma_f32_32x32x16_bf16 v[48:63], v[100:103], v[88:91], v[48:63]
	v_add_f32_e64 v80, v196, v64
	v_add_f32_e64 v81, v197, v65
	v_cvt_pk_bf16_f32 v64, v191, v193
	v_cvt_pk_bf16_f32 v65, v195, v197
	s_waitcnt lgkmcnt(0)
	v_mfma_f32_32x32x16_bf16 v[32:47], v[122:125], v[88:91], v[32:47]
	v_exp_f32_e32 v105, v72
	v_pk_add_f32 v[68:69], v[198:199], v[80:81]
	v_exp_f32_e32 v109, v73
	v_pk_add_f32 v[68:69], v[200:201], v[68:69]
	v_exp_f32_e32 v107, v74
	v_pk_add_f32 v[68:69], v[202:203], v[68:69]
	v_exp_f32_e32 v117, v75
	v_pk_add_f32 v[68:69], v[204:205], v[68:69]
	v_exp_f32_e32 v111, v76
	v_pk_add_f32 v[68:69], v[104:105], v[68:69]
	v_exp_f32_e32 v121, v77
	v_pk_add_f32 v[68:69], v[108:109], v[68:69]
	v_exp_f32_e32 v119, v78
	v_exp_f32_e32 v72, v79
	v_pk_add_f32 v[68:69], v[106:107], v[68:69]
	v_pk_add_f32 v[70:71], v[114:115], v[114:115] op_sel:[0,1] op_sel_hi:[1,0]
	v_pk_add_f32 v[68:69], v[116:117], v[68:69]
	v_mov_b32_e32 v71, v72
	v_pk_add_f32 v[68:69], v[110:111], v[68:69]
	s_nop 0
	v_pk_add_f32 v[68:69], v[120:121], v[68:69]
	s_nop 0
	v_pk_add_f32 v[68:69], v[118:119], v[68:69]
	s_nop 0
	v_pk_add_f32 v[68:69], v[70:71], v[68:69]
	v_cvt_pk_bf16_f32 v70, v111, v121
	v_add_f32_e32 v73, v68, v69
	v_cvt_pk_bf16_f32 v68, v105, v109
	v_cvt_pk_bf16_f32 v69, v107, v117
	v_cvt_pk_bf16_f32 v71, v119, v72
	v_mfma_f32_32x32x16_bf16 v[16:31], v[84:87], v[64:67], v[16:31]
	s_barrier
	s_lshl_b64 s[4:5], s[4:5], 11
	s_add_u32 s4, s88, s4
	s_addc_u32 s5, s89, s5
	s_add_u32 s4, s4, s9
	v_mfma_f32_32x32x16_bf16 v[0:15], v[96:99], v[64:67], v[0:15]
	ds_bpermute_b32 v64, v220, v93
	ds_bpermute_b32 v65, v220, v73
	s_addc_u32 s5, s5, 0
	v_mov_b32_e32 v147, v161
	s_add_i32 s8, s8, s90
	s_waitcnt lgkmcnt(1)
	v_add_f32_e32 v64, v93, v64
	v_div_scale_f32 v66, s[6:7], v64, v64, 1.0
	v_rcp_f32_e32 v67, v66
	v_mfma_f32_32x32x16_bf16 v[16:31], v[100:103], v[68:71], v[16:31]
	s_waitcnt lgkmcnt(0)
	v_add_f32_e32 v65, v73, v65
	v_lshl_add_u64 v[72:73], s[4:5], 0, v[146:147]
	v_lshl_add_u64 v[72:73], v[136:137], 1, v[72:73]
	s_mov_b64 s[4:5], 0x7a00600
	s_cmp_ge_i32 s8, s2
	v_mfma_f32_32x32x16_bf16 v[0:15], v[122:125], v[68:71], v[0:15]
	v_fma_f32 v68, -v66, v67, 1.0
	v_fmac_f32_e32 v67, v68, v67
	v_div_scale_f32 v68, vcc, 1.0, v64, 1.0
	v_mul_f32_e32 v69, v68, v67
	v_fma_f32 v70, -v66, v69, v68
	v_fmac_f32_e32 v69, v70, v67
	v_fma_f32 v66, -v66, v69, v68
	v_div_fmas_f32 v66, v66, v67, v69
	v_div_fixup_f32 v64, v66, v64, 1.0
	v_div_scale_f32 v66, s[6:7], v65, v65, v163
	v_rcp_f32_e32 v67, v66
	s_nop 0
	v_fma_f32 v68, -v66, v67, 1.0
	v_fmac_f32_e32 v67, v68, v67
	v_div_scale_f32 v68, vcc, v163, v65, v163
	v_mul_f32_e32 v69, v68, v67
	v_fma_f32 v70, -v66, v69, v68
	v_fmac_f32_e32 v69, v70, v67
	v_fma_f32 v66, -v66, v69, v68
	v_div_fmas_f32 v66, v66, v67, v69
	v_div_fixup_f32 v66, v66, v65, v163
	v_pk_mul_f32 v[12:13], v[12:13], v[66:67] op_sel_hi:[1,0]
	v_pk_mul_f32 v[14:15], v[14:15], v[66:67] op_sel_hi:[1,0]
	v_pk_fma_f32 v[12:13], v[44:45], v[64:65], v[12:13] op_sel_hi:[1,0,1] neg_lo:[0,0,1] neg_hi:[0,0,1]
	v_pk_fma_f32 v[14:15], v[46:47], v[64:65], v[14:15] op_sel_hi:[1,0,1] neg_lo:[0,0,1] neg_hi:[0,0,1]
	global_load_dwordx4 v[44:47], v[144:145], off
	v_pk_mul_f32 v[0:1], v[0:1], v[66:67] op_sel_hi:[1,0]
	v_pk_mul_f32 v[16:17], v[16:17], v[66:67] op_sel_hi:[1,0]
	v_pk_fma_f32 v[32:33], v[32:33], v[64:65], v[0:1] op_sel_hi:[1,0,1] neg_lo:[0,0,1] neg_hi:[0,0,1]
	v_pk_mul_f32 v[0:1], v[6:7], v[66:67] op_sel_hi:[1,0]
; DI float shx_(int lane, float v, int m) { return __builtin_bit_cast(float, __builtin_amdgcn_ds_bpermute((lane ^ m) << 2, __builtin_bit_cast(int, v))); }
; DI unsigned pkbf(float a, float b) { fv2 v = {a, b}; return __builtin_bit_cast(unsigned, __builtin_convertvector(v, bfv2)); }
; DI void diff_mfma_phase(const Args& A, int wave_s, int l, bool need_ctx, LAS unsigned char* lds) {
;     ...
;         float ss = 0.f;
; #pragma unroll
;         for (int mt = 0; mt < 2; ++mt)
; #pragma unroll
;             for (int i = 0; i < 16; ++i) { const float o = O[0][mt][i] * inv0 - O[1][mt][i] * inv1; O[0][mt][i] = o; ss += o * o; }
;         ss += shx_(C.lane, ss, 32);
;         const float rs = rsqrtf(ss * (1.f / 64.f) + EPS) * (1.f - lam_init);
;         bf16* op = C.MIX + (size_t)qrow0 * 1024 + 768 + hd * 64 + (unsigned)((wave * 32 + r) * 1024);
; #pragma unroll
;         for (int mt = 0; mt < 2; ++mt)
; #pragma unroll
;             for (int g = 0; g < 4; ++g) { const int dv0 = 32 * mt + 8 * g + 4 * h; const f32x4 og = *(const f32x4*)(C.dog + l * 64 + dv0);
;                 v2u w; w.x = pkbf(O[0][mt][4 * g] * rs * og.x, O[0][mt][4 * g + 1] * rs * og.y); w.y = pkbf(O[0][mt][4 * g + 2] * rs * og.z, O[0][mt][4 * g + 3] * rs * og.w);
;                 *(v2u*)(op + dv0) = w; }
;     }
	v_pk_mul_f32 v[18:19], v[18:19], v[66:67] op_sel_hi:[1,0]
	v_pk_fma_f32 v[48:49], v[48:49], v[64:65], v[16:17] op_sel_hi:[1,0,1] neg_lo:[0,0,1] neg_hi:[0,0,1]
	v_pk_fma_f32 v[6:7], v[38:39], v[64:65], v[0:1] op_sel_hi:[1,0,1] neg_lo:[0,0,1] neg_hi:[0,0,1]
	v_pk_mul_f32 v[0:1], v[4:5], v[66:67] op_sel_hi:[1,0]
	v_pk_fma_f32 v[18:19], v[50:51], v[64:65], v[18:19] op_sel_hi:[1,0,1] neg_lo:[0,0,1] neg_hi:[0,0,1]
	v_pk_mul_f32 v[74:75], v[48:49], v[48:49]
	v_pk_fma_f32 v[36:37], v[36:37], v[64:65], v[0:1] op_sel_hi:[1,0,1] neg_lo:[0,0,1] neg_hi:[0,0,1]
	v_pk_mul_f32 v[0:1], v[10:11], v[66:67] op_sel_hi:[1,0]
	v_pk_mul_f32 v[50:51], v[18:19], v[18:19]
	v_pk_mul_f32 v[20:21], v[20:21], v[66:67] op_sel_hi:[1,0]
	v_pk_fma_f32 v[0:1], v[42:43], v[64:65], v[0:1] op_sel_hi:[1,0,1] neg_lo:[0,0,1] neg_hi:[0,0,1]
	v_add_f32_e32 v42, v74, v75
	v_pk_fma_f32 v[20:21], v[52:53], v[64:65], v[20:21] op_sel_hi:[1,0,1] neg_lo:[0,0,1] neg_hi:[0,0,1]
	v_add_f32_e32 v42, v50, v42
	v_pk_mul_f32 v[22:23], v[22:23], v[66:67] op_sel_hi:[1,0]
	v_pk_mul_f32 v[52:53], v[20:21], v[20:21]
	v_add_f32_e32 v42, v51, v42
	v_pk_fma_f32 v[22:23], v[54:55], v[64:65], v[22:23] op_sel_hi:[1,0,1] neg_lo:[0,0,1] neg_hi:[0,0,1]
	v_add_f32_e32 v42, v52, v42
	v_pk_mul_f32 v[54:55], v[22:23], v[22:23]
	v_pk_mul_f32 v[24:25], v[24:25], v[66:67] op_sel_hi:[1,0]
	v_add_f32_e32 v42, v53, v42
	v_pk_fma_f32 v[24:25], v[56:57], v[64:65], v[24:25] op_sel_hi:[1,0,1] neg_lo:[0,0,1] neg_hi:[0,0,1]
	v_add_f32_e32 v42, v54, v42
	v_pk_mul_f32 v[26:27], v[26:27], v[66:67] op_sel_hi:[1,0]
	v_pk_mul_f32 v[56:57], v[24:25], v[24:25]
	v_add_f32_e32 v42, v55, v42
	v_pk_fma_f32 v[26:27], v[58:59], v[64:65], v[26:27] op_sel_hi:[1,0,1] neg_lo:[0,0,1] neg_hi:[0,0,1]
	v_add_f32_e32 v42, v56, v42
	v_pk_mul_f32 v[58:59], v[26:27], v[26:27]
	v_pk_mul_f32 v[28:29], v[28:29], v[66:67] op_sel_hi:[1,0]
	v_add_f32_e32 v42, v57, v42
	v_pk_fma_f32 v[28:29], v[60:61], v[64:65], v[28:29] op_sel_hi:[1,0,1] neg_lo:[0,0,1] neg_hi:[0,0,1]
	v_add_f32_e32 v42, v58, v42
	v_pk_mul_f32 v[30:31], v[30:31], v[66:67] op_sel_hi:[1,0]
	v_pk_mul_f32 v[60:61], v[28:29], v[28:29]
	v_add_f32_e32 v42, v59, v42
	v_pk_fma_f32 v[30:31], v[62:63], v[64:65], v[30:31] op_sel_hi:[1,0,1] neg_lo:[0,0,1] neg_hi:[0,0,1]
	v_add_f32_e32 v42, v60, v42
	v_pk_mul_f32 v[62:63], v[30:31], v[30:31]
	v_add_f32_e32 v42, v61, v42
	v_add_f32_e32 v42, v62, v42
	v_pk_mul_f32 v[2:3], v[2:3], v[66:67] op_sel_hi:[1,0]
	v_pk_mul_f32 v[76:77], v[32:33], v[32:33]
	v_add_f32_e32 v42, v63, v42
	v_pk_fma_f32 v[34:35], v[34:35], v[64:65], v[2:3] op_sel_hi:[1,0,1] neg_lo:[0,0,1] neg_hi:[0,0,1]
	v_add_f32_e32 v42, v76, v42
	v_pk_mul_f32 v[2:3], v[34:35], v[34:35]
	v_add_f32_e32 v42, v77, v42
	v_add_f32_e32 v2, v2, v42
	v_pk_mul_f32 v[4:5], v[36:37], v[36:37]
	v_add_f32_e32 v2, v3, v2
	v_add_f32_e32 v2, v4, v2
	v_pk_mul_f32 v[38:39], v[6:7], v[6:7]
	v_pk_mul_f32 v[8:9], v[8:9], v[66:67] op_sel_hi:[1,0]
	v_add_f32_e32 v2, v5, v2
	v_pk_fma_f32 v[8:9], v[40:41], v[64:65], v[8:9] op_sel_hi:[1,0,1] neg_lo:[0,0,1] neg_hi:[0,0,1]
	v_add_f32_e32 v2, v38, v2
	v_pk_mul_f32 v[40:41], v[8:9], v[8:9]
	v_add_f32_e32 v2, v39, v2
	v_add_f32_e32 v2, v40, v2
	v_pk_mul_f32 v[10:11], v[0:1], v[0:1]
	v_add_f32_e32 v2, v41, v2
	v_add_f32_e32 v2, v10, v2
	v_pk_mul_f32 v[68:69], v[12:13], v[12:13]
	v_add_f32_e32 v2, v11, v2
	v_add_f32_e32 v2, v68, v2
	v_pk_mul_f32 v[70:71], v[14:15], v[14:15]
	v_add_f32_e32 v2, v69, v2
	v_add_f32_e32 v2, v70, v2
	v_add_f32_e32 v2, v71, v2
	ds_bpermute_b32 v3, v220, v2
	v_lshl_add_u64 v[16:17], v[72:73], 0, s[4:5]
	s_mov_b32 s4, 0x7a00000
	s_waitcnt lgkmcnt(0)
	v_add_f32_e32 v2, v2, v3
	v_fmamk_f32 v2, v2, 0x3c800000, v162
	v_cmp_gt_f32_e32 vcc, s78, v2
	v_mul_f32_e32 v3, 0x4b800000, v2
	s_nop 0
	v_cndmask_b32_e32 v2, v2, v3, vcc
	v_rsq_f32_e32 v2, v2
	s_nop 0
	v_mul_f32_e32 v3, 0x45800000, v2
	v_cndmask_b32_e32 v2, v2, v3, vcc
	v_mul_f32_e32 v10, v221, v2
	v_pk_mul_f32 v[2:3], v[48:49], v[10:11] op_sel_hi:[1,0]
	v_pk_mul_f32 v[4:5], v[18:19], v[10:11] op_sel_hi:[1,0]
	s_waitcnt vmcnt(0)
	v_pk_mul_f32 v[2:3], v[44:45], v[2:3]
	v_pk_mul_f32 v[4:5], v[46:47], v[4:5]
	v_cvt_pk_bf16_f32 v2, v2, v3
	v_cvt_pk_bf16_f32 v3, v4, v5
	v_add_co_u32_e32 v4, vcc, s4, v72
	v_pk_mul_f32 v[18:19], v[20:21], v[10:11] op_sel_hi:[1,0]
	s_nop 0
	v_addc_co_u32_e32 v5, vcc, 0, v73, vcc
	global_store_dwordx2 v[4:5], v[2:3], off offset:1536
	global_load_dwordx4 v[2:5], v[144:145], off offset:32
	v_pk_mul_f32 v[6:7], v[6:7], v[10:11] op_sel_hi:[1,0]
	v_pk_mul_f32 v[0:1], v[0:1], v[10:11] op_sel_hi:[1,0]
	s_waitcnt vmcnt(0)
	v_pk_mul_f32 v[2:3], v[2:3], v[18:19]
	v_pk_mul_f32 v[18:19], v[22:23], v[10:11] op_sel_hi:[1,0]
	v_cvt_pk_bf16_f32 v2, v2, v3
	v_pk_mul_f32 v[4:5], v[4:5], v[18:19]
	v_pk_mul_f32 v[18:19], v[24:25], v[10:11] op_sel_hi:[1,0]
	v_cvt_pk_bf16_f32 v3, v4, v5
	global_store_dwordx2 v[16:17], v[2:3], off offset:16
	global_load_dwordx4 v[2:5], v[144:145], off offset:64
	s_waitcnt vmcnt(0)
	v_pk_mul_f32 v[2:3], v[2:3], v[18:19]
	v_pk_mul_f32 v[18:19], v[26:27], v[10:11] op_sel_hi:[1,0]
	v_cvt_pk_bf16_f32 v2, v2, v3
	v_pk_mul_f32 v[4:5], v[4:5], v[18:19]
	v_pk_mul_f32 v[18:19], v[28:29], v[10:11] op_sel_hi:[1,0]
	v_cvt_pk_bf16_f32 v3, v4, v5
	global_store_dwordx2 v[16:17], v[2:3], off offset:32
	global_load_dwordx4 v[2:5], v[144:145], off offset:96
	s_waitcnt vmcnt(0)
	v_pk_mul_f32 v[2:3], v[2:3], v[18:19]
	v_pk_mul_f32 v[18:19], v[30:31], v[10:11] op_sel_hi:[1,0]
	v_cvt_pk_bf16_f32 v2, v2, v3
	v_pk_mul_f32 v[4:5], v[4:5], v[18:19]
	v_pk_mul_f32 v[18:19], v[32:33], v[10:11] op_sel_hi:[1,0]
	v_cvt_pk_bf16_f32 v3, v4, v5
	global_store_dwordx2 v[16:17], v[2:3], off offset:48
	global_load_dwordx4 v[2:5], v[144:145], off offset:128
	s_waitcnt vmcnt(0)
	v_pk_mul_f32 v[2:3], v[2:3], v[18:19]
	v_pk_mul_f32 v[18:19], v[34:35], v[10:11] op_sel_hi:[1,0]
	v_cvt_pk_bf16_f32 v2, v2, v3
	v_pk_mul_f32 v[4:5], v[4:5], v[18:19]
	v_pk_mul_f32 v[18:19], v[36:37], v[10:11] op_sel_hi:[1,0]
	v_cvt_pk_bf16_f32 v3, v4, v5
	global_store_dwordx2 v[16:17], v[2:3], off offset:64
	global_load_dwordx4 v[2:5], v[144:145], off offset:160
	s_waitcnt vmcnt(0)
	v_pk_mul_f32 v[2:3], v[2:3], v[18:19]
	v_pk_mul_f32 v[4:5], v[4:5], v[6:7]
	v_cvt_pk_bf16_f32 v2, v2, v3
	v_cvt_pk_bf16_f32 v3, v4, v5
	global_store_dwordx2 v[16:17], v[2:3], off offset:80
	global_load_dwordx4 v[2:5], v[144:145], off offset:192
	v_pk_mul_f32 v[6:7], v[8:9], v[10:11] op_sel_hi:[1,0]
	s_waitcnt vmcnt(0)
	v_pk_mul_f32 v[0:1], v[4:5], v[0:1]
	v_pk_mul_f32 v[2:3], v[2:3], v[6:7]
	v_pk_mul_f32 v[4:5], v[12:13], v[10:11] op_sel_hi:[1,0]
	v_cvt_pk_bf16_f32 v2, v2, v3
	v_cvt_pk_bf16_f32 v3, v0, v1
	global_store_dwordx2 v[16:17], v[2:3], off offset:96
	global_load_dwordx4 v[0:3], v[144:145], off offset:224
	s_waitcnt vmcnt(0)
	v_pk_mul_f32 v[0:1], v[0:1], v[4:5]
	v_pk_mul_f32 v[4:5], v[14:15], v[10:11] op_sel_hi:[1,0]
	v_cvt_pk_bf16_f32 v0, v0, v1
	v_pk_mul_f32 v[2:3], v[2:3], v[4:5]
	s_nop 0
	v_cvt_pk_bf16_f32 v1, v2, v3
	global_store_dwordx2 v[16:17], v[0:1], off offset:112
	s_cbranch_scc0 .LBB0_401
